# softmax row-max as two interleaved v_max3 chains (shorter dependent chain), one more redundant v_max and a no-op s_add removed
# speedup vs baseline: 1.0200x; 1.0007x over previous
; template <bool WIN>
; __device__ __forceinline__ void partialSM(f32x16& p0, f32x16& p1, float& m_reg, float& mn, float& alpha) {
;   constexpr float C = SCALE * 1.4426950408889634f;
;   float pmax = p0[0];
; #pragma unroll
;   for (int r = 1; r < 16; ++r) pmax = fmaxf(pmax, p0[r]);
; #pragma unroll
;   for (int r = 0; r < 16; ++r) pmax = fmaxf(pmax, p1[r]);
;   { auto rr = __builtin_amdgcn_permlane32_swap(__float_as_uint(pmax), __float_as_uint(pmax), false, false);
;     pmax = fmaxf(__uint_as_float(rr[0]), __uint_as_float(rr[1])); }
;   if (__builtin_expect(__all(pmax - m_reg <= THR / SCALE), 1)) { mn = m_reg; alpha = 1.f; }
;   else { mn = fmaxf(m_reg, pmax); alpha = __builtin_amdgcn_exp2f((m_reg - mn) * C); m_reg = mn; }
;   float mnC = -mn * C;
; #pragma unroll
;   for (int r = 0; r < 16; ++r) p0[r] = fmaf(p0[r], C, mnC);
; #pragma unroll
;   for (int r = 0; r < 16; ++r) p1[r] = fmaf(p1[r], C, mnC);
; template <bool WIN>
; __device__ __forceinline__ void qkt(f32x16& p0, f32x16& p1, const bf16_t* Ks, const bf16x8* qr, int r32, int hi, int dq) {
;   p0 = f32x16{}; p1 = f32x16{};
;   if (WIN) {
;     const int t = 4 * hi - dq + 128;
; #pragma unroll
;     for (int r = 0; r < 16; ++r) { const unsigned d0 = (unsigned)(t + (r & 3) + 8 * (r >> 2)), d1 = d0 + 32u;
;       p0[r] = d0 > 256u ? -1e30f : 0.f; p1[r] = d1 > 256u ? -1e30f : 0.f; }
;   }
; #pragma unroll
;   for (int d0 = 0; d0 < 8; ++d0) { int cb = (d0 * 16 + hi * 8) * 2;
;     bf16x8 b0 = *reinterpret_cast<const bf16x8*>((const char*)Ks + KSWZ(r32, cb));
;     bf16x8 b1 = *reinterpret_cast<const bf16x8*>((const char*)Ks + KSWZ(32 + r32, cb));
;     p0 = __builtin_amdgcn_mfma_f32_32x32x16_bf16(b0, qr[d0], p0, 0, 0, 0);
;     p1 = __builtin_amdgcn_mfma_f32_32x32x16_bf16(b1, qr[d0], p1, 0, 0, 0); }
.LBB0_643:
	s_and_b32 s69, s68, 1
	s_xor_b32 s33, s69, 1
	s_lshl_b32 s0, s33, 14
	s_add_i32 s0, s35, s0
	v_lshl_add_u64 v[254:255], s[22:23], 0, v[206:207]
	s_mov_b32 m0, s0
	s_nop 0
	global_load_lds_dwordx4 v[254:255], off
	v_lshl_add_u64 v[254:255], s[22:23], 0, v[204:205]
	s_add_i32 m0, s0, 0x400
	s_nop 0
	global_load_lds_dwordx4 v[254:255], off
	s_setprio 1
	s_lshl_b32 s0, s69, 14
	v_add3_u32 v0, s0, v209, v199
	ds_read_b128 v[130:133], v0
	ds_read_b128 v[134:137], v0 offset:8192
	v_add3_u32 v0, s0, v210, v199
	ds_read_b128 v[232:235], v0
	ds_read_b128 v[236:239], v0 offset:8192
	v_add3_u32 v0, s0, v211, v199
	ds_read_b128 v[246:249], v0
	ds_read_b128 v[250:253], v0 offset:8192
	s_waitcnt lgkmcnt(4)
	v_mfma_f32_32x32x16_bf16 v[146:161], v[130:133], v[162:165], 0
	v_mfma_f32_32x32x16_bf16 v[130:145], v[134:137], v[162:165], 0
	s_waitcnt lgkmcnt(2)
	v_mfma_f32_32x32x16_bf16 v[146:161], v[232:235], v[166:169], v[146:161]
	v_mfma_f32_32x32x16_bf16 v[130:145], v[236:239], v[166:169], v[130:145]
	v_add3_u32 v0, s0, v212, v199
	ds_read_b128 v[232:235], v0
	ds_read_b128 v[236:239], v0 offset:8192
	s_waitcnt lgkmcnt(2)
	v_mfma_f32_32x32x16_bf16 v[146:161], v[246:249], v[170:173], v[146:161]
	v_mfma_f32_32x32x16_bf16 v[130:145], v[250:253], v[170:173], v[130:145]
	v_add3_u32 v0, s0, v213, v199
	ds_read_b128 v[246:249], v0
	ds_read_b128 v[250:253], v0 offset:8192
	s_waitcnt lgkmcnt(2)
	v_mfma_f32_32x32x16_bf16 v[146:161], v[232:235], v[174:177], v[146:161]
	v_mfma_f32_32x32x16_bf16 v[130:145], v[236:239], v[174:177], v[130:145]
	v_add3_u32 v0, s0, v214, v199
	ds_read_b128 v[232:235], v0
	ds_read_b128 v[236:239], v0 offset:8192
	s_waitcnt lgkmcnt(2)
	v_mfma_f32_32x32x16_bf16 v[146:161], v[246:249], v[178:181], v[146:161]
	v_mfma_f32_32x32x16_bf16 v[130:145], v[250:253], v[178:181], v[130:145]
	v_add3_u32 v0, s0, v215, v199
	ds_read_b128 v[246:249], v0
	ds_read_b128 v[250:253], v0 offset:8192
	s_waitcnt lgkmcnt(2)
	v_mfma_f32_32x32x16_bf16 v[146:161], v[232:235], v[182:185], v[146:161]
	v_mfma_f32_32x32x16_bf16 v[130:145], v[236:239], v[182:185], v[130:145]
	v_add3_u32 v0, s0, v216, v199
	ds_read_b128 v[232:235], v0
	ds_read_b128 v[236:239], v0 offset:8192
	s_waitcnt lgkmcnt(2)
	v_mfma_f32_32x32x16_bf16 v[146:161], v[246:249], v[186:189], v[146:161]
	v_mfma_f32_32x32x16_bf16 v[130:145], v[250:253], v[186:189], v[130:145]
	s_waitcnt lgkmcnt(0)
	v_mfma_f32_32x32x16_bf16 v[146:161], v[232:235], v[190:193], v[146:161]
	v_mfma_f32_32x32x16_bf16 v[130:145], v[236:239], v[190:193], v[130:145]
	s_setprio 0
	s_nop 7
	s_nop 3
	v_max3_f32 v0, v146, v147, v148
	v_max3_f32 v231, v130, v131, v132
	v_max3_f32 v0, v0, v149, v150
	v_max3_f32 v231, v231, v133, v134
	v_max3_f32 v0, v0, v151, v152
	v_max3_f32 v231, v231, v135, v136
	v_max3_f32 v0, v0, v153, v154
	v_max3_f32 v231, v231, v137, v138
	v_max3_f32 v0, v0, v155, v156
	v_max3_f32 v231, v231, v139, v140
	v_max3_f32 v0, v0, v157, v158
	v_max3_f32 v231, v231, v141, v142
	v_max3_f32 v0, v0, v159, v160
	v_max3_f32 v231, v231, v143, v144
	v_max3_f32 v0, v0, v161, v231
	v_max_f32_e32 v0, v0, v145
	v_mov_b32_e32 v231, v0
	s_nop 1
	v_permlane32_swap_b32_e32 v0, v231
	v_max_f32_e32 v0, v0, v231
	v_sub_f32_e32 v231, v0, v229
	s_mov_b32 s0, 0x42b504f3
	v_cmp_ge_f32_e32 vcc, s0, v231
	v_max_f32_e32 v232, v229, v0
	s_cmp_eq_u64 vcc, exec
	s_cselect_b64 vcc, -1, 0
	v_sub_f32_e32 v0, v229, v232
	v_cndmask_b32_e32 v229, v232, v229, vcc
	v_mul_f32_e32 v231, 0xbe0293ee, v229
	v_fmamk_f32 v146, v146, 0x3e0293ee, v231
	v_fmamk_f32 v147, v147, 0x3e0293ee, v231
	v_fmamk_f32 v148, v148, 0x3e0293ee, v231
	v_fmamk_f32 v149, v149, 0x3e0293ee, v231
	v_fmamk_f32 v150, v150, 0x3e0293ee, v231
	v_fmamk_f32 v151, v151, 0x3e0293ee, v231
	v_fmamk_f32 v152, v152, 0x3e0293ee, v231
	v_fmamk_f32 v153, v153, 0x3e0293ee, v231
	v_fmamk_f32 v154, v154, 0x3e0293ee, v231
	v_fmamk_f32 v155, v155, 0x3e0293ee, v231
	v_fmamk_f32 v156, v156, 0x3e0293ee, v231
	v_fmamk_f32 v157, v157, 0x3e0293ee, v231
	v_fmamk_f32 v158, v158, 0x3e0293ee, v231
	v_fmamk_f32 v159, v159, 0x3e0293ee, v231
	v_fmamk_f32 v160, v160, 0x3e0293ee, v231
	v_fmamk_f32 v161, v161, 0x3e0293ee, v231
	v_fmamk_f32 v130, v130, 0x3e0293ee, v231
	v_fmamk_f32 v131, v131, 0x3e0293ee, v231
	v_fmamk_f32 v132, v132, 0x3e0293ee, v231
	v_fmamk_f32 v133, v133, 0x3e0293ee, v231
	v_fmamk_f32 v134, v134, 0x3e0293ee, v231
	v_fmamk_f32 v135, v135, 0x3e0293ee, v231
	v_fmamk_f32 v136, v136, 0x3e0293ee, v231
	v_fmamk_f32 v137, v137, 0x3e0293ee, v231
	v_fmamk_f32 v138, v138, 0x3e0293ee, v231
	v_fmamk_f32 v139, v139, 0x3e0293ee, v231
	v_fmamk_f32 v140, v140, 0x3e0293ee, v231
	v_fmamk_f32 v141, v141, 0x3e0293ee, v231
	v_fmamk_f32 v142, v142, 0x3e0293ee, v231
	v_fmamk_f32 v143, v143, 0x3e0293ee, v231
	v_fmamk_f32 v144, v144, 0x3e0293ee, v231
	v_fmac_f32_e32 v231, 0x3e0293ee, v145
	v_exp_f32_e32 v145, v146
	v_exp_f32_e32 v146, v147
	v_exp_f32_e32 v147, v148
	v_exp_f32_e32 v148, v149
	v_exp_f32_e32 v149, v150
	v_exp_f32_e32 v150, v151
	v_exp_f32_e32 v151, v152
	v_exp_f32_e32 v152, v153
	v_exp_f32_e32 v153, v154
	v_exp_f32_e32 v154, v155
	v_exp_f32_e32 v155, v156
	v_exp_f32_e32 v156, v157
	v_exp_f32_e32 v157, v158
	v_exp_f32_e32 v158, v159
	v_exp_f32_e32 v159, v160
	v_exp_f32_e32 v160, v161
	v_exp_f32_e32 v161, v134
	v_add_f32_e32 v134, v146, v145
	v_add_f32_e32 v134, v147, v134
	v_add_f32_e32 v134, v148, v134
	v_add_f32_e32 v134, v149, v134
	v_add_f32_e32 v134, v150, v134
	v_add_f32_e32 v134, v151, v134
	v_add_f32_e32 v134, v152, v134
	v_add_f32_e32 v134, v153, v134
; __device__ __forceinline__ void finishSM(f32x16& p0, f32x16& p1, float alpha, float& l_reg, bf16x8& pa0, bf16x8& pa1, bf16x8& pa2, bf16x8& pa3) {
; #pragma unroll
;   for (int r = 0; r < 16; ++r) p1[r] = __builtin_amdgcn_exp2f(p1[r]);
;   float ps = 0;
; #pragma unroll
;   for (int r = 0; r < 16; ++r) ps += p0[r];
; #pragma unroll
;   for (int r = 0; r < 16; ++r) ps += p1[r];
;   { auto rr = __builtin_amdgcn_permlane32_swap(__float_as_uint(ps), __float_as_uint(ps), false, false);
;     ps = __uint_as_float(rr[0]) + __uint_as_float(rr[1]); }
;   l_reg = l_reg * alpha + ps;
;     ...
;   PK4(p0, 0, pa0); PK4(p0, 8, pa1); PK4(p1, 0, pa2); PK4(p1, 8, pa3);
	v_add_f32_e32 v134, v154, v134
	v_add_f32_e32 v134, v155, v134
	v_add_f32_e32 v134, v156, v134
	v_exp_f32_e32 v130, v130
	v_add_f32_e32 v134, v157, v134
	v_exp_f32_e32 v131, v131
	v_add_f32_e32 v134, v158, v134
	v_exp_f32_e32 v132, v132
	v_add_f32_e32 v134, v159, v134
	v_exp_f32_e32 v133, v133
	v_add_f32_e32 v134, v160, v134
	v_add_f32_e32 v134, v130, v134
	v_exp_f32_e32 v233, v135
	v_add_f32_e32 v134, v131, v134
	v_exp_f32_e32 v234, v136
	v_add_f32_e32 v134, v132, v134
	v_exp_f32_e32 v235, v137
	v_add_f32_e32 v134, v133, v134
	v_exp_f32_e32 v138, v138
	v_add_f32_e32 v134, v161, v134
	v_exp_f32_e32 v139, v139
	v_add_f32_e32 v134, v233, v134
	v_exp_f32_e32 v140, v140
	v_add_f32_e32 v134, v234, v134
	v_exp_f32_e32 v141, v141
	v_add_f32_e32 v134, v235, v134
	v_exp_f32_e32 v236, v142
	v_add_f32_e32 v134, v138, v134
	v_exp_f32_e32 v237, v143
	v_add_f32_e32 v134, v139, v134
	v_exp_f32_e32 v238, v144
	v_add_f32_e32 v134, v140, v134
	v_mul_f32_e32 v0, 0x3e0293ee, v0
	v_exp_f32_e32 v239, v231
	v_add_f32_e32 v134, v141, v134
	v_exp_f32_e32 v0, v0
	v_add_f32_e32 v134, v236, v134
	v_add_f32_e32 v134, v237, v134
	v_add_f32_e32 v134, v238, v134
	v_add_f32_e32 v231, v239, v134
	v_cndmask_b32_e64 v0, v0, 1.0, vcc
	v_mov_b32_e32 v232, v231
	v_cvt_pk_bf16_f32 v134, v145, v146
	v_cvt_pk_bf16_f32 v135, v147, v148
	v_cvt_pk_bf16_f32 v136, v149, v150
	v_cvt_pk_bf16_f32 v137, v151, v152
	v_cvt_pk_bf16_f32 v142, v153, v154
	v_cvt_pk_bf16_f32 v143, v155, v156
	v_cvt_pk_bf16_f32 v144, v157, v158
	v_cvt_pk_bf16_f32 v145, v159, v160
	v_cvt_pk_bf16_f32 v130, v130, v131
	v_cvt_pk_bf16_f32 v131, v132, v133
	v_cvt_pk_bf16_f32 v132, v161, v233
	v_cvt_pk_bf16_f32 v133, v234, v235
	v_cvt_pk_bf16_f32 v138, v138, v139
	v_cvt_pk_bf16_f32 v139, v140, v141
	v_cvt_pk_bf16_f32 v140, v236, v237
	v_cvt_pk_bf16_f32 v141, v238, v239
	v_permlane32_swap_b32_e32 v231, v232
	v_permlane32_swap_b32_e32 v134, v136
	v_permlane32_swap_b32_e32 v135, v137
	v_permlane32_swap_b32_e32 v142, v144
	v_permlane32_swap_b32_e32 v143, v145
	v_permlane32_swap_b32_e32 v130, v132
	v_permlane32_swap_b32_e32 v131, v133
	v_permlane32_swap_b32_e32 v138, v140
	v_permlane32_swap_b32_e32 v139, v141
	v_cmp_gt_f32_e32 vcc, 1.0, v0
	s_cbranch_vccz .LBB0_649
	s_and_saveexec_b64 s[0:1], s[6:7]
	ds_write_b32 v228, v0 offset:128
	s_or_b64 exec, exec, s[0:1]
	s_waitcnt lgkmcnt(0)
	v_add_u32_e32 v146, s67, v223
	ds_read_b128 v[158:161], v146 offset:224
	ds_read_b128 v[154:157], v146 offset:192
	ds_read_b128 v[150:153], v146 offset:160
	ds_read_b128 v[146:149], v146 offset:128
	s_waitcnt lgkmcnt(0)
	v_pk_mul_f32 v[126:127], v[126:127], v[158:159]
	v_pk_mul_f32 v[122:123], v[122:123], v[154:155]
	v_pk_mul_f32 v[118:119], v[118:119], v[150:151]
	v_pk_mul_f32 v[128:129], v[128:129], v[160:161]
	v_pk_mul_f32 v[124:125], v[124:125], v[156:157]
	v_pk_mul_f32 v[120:121], v[120:121], v[152:153]
	v_pk_mul_f32 v[116:117], v[116:117], v[148:149]
	v_pk_mul_f32 v[114:115], v[114:115], v[146:147]
	v_pk_mul_f32 v[110:111], v[110:111], v[158:159]
	v_pk_mul_f32 v[106:107], v[106:107], v[154:155]
	v_pk_mul_f32 v[102:103], v[102:103], v[150:151]
	v_pk_mul_f32 v[112:113], v[112:113], v[160:161]
	v_pk_mul_f32 v[108:109], v[108:109], v[156:157]
	v_pk_mul_f32 v[104:105], v[104:105], v[152:153]
	v_pk_mul_f32 v[100:101], v[100:101], v[148:149]
	v_pk_mul_f32 v[98:99], v[98:99], v[146:147]
	v_pk_mul_f32 v[94:95], v[94:95], v[158:159]
	v_pk_mul_f32 v[90:91], v[90:91], v[154:155]
	v_pk_mul_f32 v[86:87], v[86:87], v[150:151]
	v_pk_mul_f32 v[96:97], v[96:97], v[160:161]
	v_pk_mul_f32 v[92:93], v[92:93], v[156:157]
	v_pk_mul_f32 v[88:89], v[88:89], v[152:153]
	v_pk_mul_f32 v[84:85], v[84:85], v[148:149]
	v_pk_mul_f32 v[82:83], v[82:83], v[146:147]
	v_pk_mul_f32 v[78:79], v[78:79], v[158:159]
	v_pk_mul_f32 v[74:75], v[74:75], v[154:155]
	v_pk_mul_f32 v[70:71], v[70:71], v[150:151]
	v_pk_mul_f32 v[80:81], v[80:81], v[160:161]
	v_pk_mul_f32 v[76:77], v[76:77], v[156:157]
	v_pk_mul_f32 v[72:73], v[72:73], v[152:153]
	v_pk_mul_f32 v[68:69], v[68:69], v[148:149]
	v_pk_mul_f32 v[66:67], v[66:67], v[146:147]
	v_pk_mul_f32 v[62:63], v[62:63], v[158:159]
	v_pk_mul_f32 v[58:59], v[58:59], v[154:155]
	v_pk_mul_f32 v[54:55], v[54:55], v[150:151]
	v_pk_mul_f32 v[64:65], v[64:65], v[160:161]
	v_pk_mul_f32 v[60:61], v[60:61], v[156:157]
	v_pk_mul_f32 v[56:57], v[56:57], v[152:153]
	v_pk_mul_f32 v[52:53], v[52:53], v[148:149]
	v_pk_mul_f32 v[50:51], v[50:51], v[146:147]
	v_pk_mul_f32 v[46:47], v[46:47], v[158:159]
	v_pk_mul_f32 v[42:43], v[42:43], v[154:155]
	v_pk_mul_f32 v[38:39], v[38:39], v[150:151]
	v_pk_mul_f32 v[48:49], v[48:49], v[160:161]
	v_pk_mul_f32 v[44:45], v[44:45], v[156:157]
	v_pk_mul_f32 v[40:41], v[40:41], v[152:153]
	v_pk_mul_f32 v[36:37], v[36:37], v[148:149]
	v_pk_mul_f32 v[34:35], v[34:35], v[146:147]
	v_pk_mul_f32 v[30:31], v[30:31], v[158:159]
	v_pk_mul_f32 v[26:27], v[26:27], v[154:155]
	v_pk_mul_f32 v[22:23], v[22:23], v[150:151]
	v_pk_mul_f32 v[32:33], v[32:33], v[160:161]
	v_pk_mul_f32 v[28:29], v[28:29], v[156:157]
	v_pk_mul_f32 v[24:25], v[24:25], v[152:153]
	v_pk_mul_f32 v[20:21], v[20:21], v[148:149]
	v_pk_mul_f32 v[18:19], v[18:19], v[146:147]
	v_pk_mul_f32 v[14:15], v[14:15], v[158:159]
	v_pk_mul_f32 v[10:11], v[10:11], v[154:155]
	v_pk_mul_f32 v[6:7], v[6:7], v[150:151]
	v_pk_mul_f32 v[16:17], v[16:17], v[160:161]
	v_pk_mul_f32 v[12:13], v[12:13], v[156:157]
	v_pk_mul_f32 v[8:9], v[8:9], v[152:153]
	v_pk_mul_f32 v[4:5], v[4:5], v[148:149]
	v_pk_mul_f32 v[2:3], v[2:3], v[146:147]

; template <bool WIN>
; __device__ __forceinline__ void partialSM(f32x16& p0, f32x16& p1, float& m_reg, float& mn, float& alpha) {
;   constexpr float C = SCALE * 1.4426950408889634f;
;   float pmax = p0[0];
; #pragma unroll
;   for (int r = 1; r < 16; ++r) pmax = fmaxf(pmax, p0[r]);
; #pragma unroll
;   for (int r = 0; r < 16; ++r) pmax = fmaxf(pmax, p1[r]);
;   { auto rr = __builtin_amdgcn_permlane32_swap(__float_as_uint(pmax), __float_as_uint(pmax), false, false);
;     pmax = fmaxf(__uint_as_float(rr[0]), __uint_as_float(rr[1])); }
;   if (__builtin_expect(__all(pmax - m_reg <= THR / SCALE), 1)) { mn = m_reg; alpha = 1.f; }
;   else { mn = fmaxf(m_reg, pmax); alpha = __builtin_amdgcn_exp2f((m_reg - mn) * C); m_reg = mn; }
;   float mnC = -mn * C;
; #pragma unroll
;   for (int r = 0; r < 16; ++r) p0[r] = fmaf(p0[r], C, mnC);
; #pragma unroll
;   for (int r = 0; r < 16; ++r) p1[r] = fmaf(p1[r], C, mnC);
; template <bool WIN>
; __device__ __forceinline__ void qkt(f32x16& p0, f32x16& p1, const bf16_t* Ks, const bf16x8* qr, int r32, int hi, int dq) {
;   p0 = f32x16{}; p1 = f32x16{};
;   if (WIN) {
;     const int t = 4 * hi - dq + 128;
; #pragma unroll
;     for (int r = 0; r < 16; ++r) { const unsigned d0 = (unsigned)(t + (r & 3) + 8 * (r >> 2)), d1 = d0 + 32u;
;       p0[r] = d0 > 256u ? -1e30f : 0.f; p1[r] = d1 > 256u ? -1e30f : 0.f; }
;   }
; #pragma unroll
;   for (int d0 = 0; d0 < 8; ++d0) { int cb = (d0 * 16 + hi * 8) * 2;
;     bf16x8 b0 = *reinterpret_cast<const bf16x8*>((const char*)Ks + KSWZ(r32, cb));
;     bf16x8 b1 = *reinterpret_cast<const bf16x8*>((const char*)Ks + KSWZ(32 + r32, cb));
;     p0 = __builtin_amdgcn_mfma_f32_32x32x16_bf16(b0, qr[d0], p0, 0, 0, 0);
;     p1 = __builtin_amdgcn_mfma_f32_32x32x16_bf16(b1, qr[d0], p1, 0, 0, 0); }
.Lpl_top:
	s_and_b32 s69, s68, 1
	s_setprio 1
	s_lshl_b32 s0, s69, 14
	v_add3_u32 v0, s0, v209, v199
	ds_read_b128 v[130:133], v0
	ds_read_b128 v[134:137], v0 offset:8192
	v_add3_u32 v0, s0, v210, v199
	ds_read_b128 v[232:235], v0
	ds_read_b128 v[236:239], v0 offset:8192
	v_add3_u32 v0, s0, v211, v199
	ds_read_b128 v[246:249], v0
	ds_read_b128 v[250:253], v0 offset:8192
	s_waitcnt lgkmcnt(4)
	v_mfma_f32_32x32x16_bf16 v[146:161], v[130:133], v[162:165], 0
	v_mfma_f32_32x32x16_bf16 v[130:145], v[134:137], v[162:165], 0
	s_waitcnt lgkmcnt(2)
	v_mfma_f32_32x32x16_bf16 v[146:161], v[232:235], v[166:169], v[146:161]
	v_mfma_f32_32x32x16_bf16 v[130:145], v[236:239], v[166:169], v[130:145]
	v_add3_u32 v0, s0, v212, v199
	ds_read_b128 v[232:235], v0
	ds_read_b128 v[236:239], v0 offset:8192
	s_waitcnt lgkmcnt(2)
	v_mfma_f32_32x32x16_bf16 v[146:161], v[246:249], v[170:173], v[146:161]
	v_mfma_f32_32x32x16_bf16 v[130:145], v[250:253], v[170:173], v[130:145]
	v_add3_u32 v0, s0, v213, v199
	ds_read_b128 v[246:249], v0
	ds_read_b128 v[250:253], v0 offset:8192
	s_waitcnt lgkmcnt(2)
	v_mfma_f32_32x32x16_bf16 v[146:161], v[232:235], v[174:177], v[146:161]
	v_mfma_f32_32x32x16_bf16 v[130:145], v[236:239], v[174:177], v[130:145]
	v_add3_u32 v0, s0, v214, v199
	ds_read_b128 v[232:235], v0
	ds_read_b128 v[236:239], v0 offset:8192
	s_waitcnt lgkmcnt(2)
	v_mfma_f32_32x32x16_bf16 v[146:161], v[246:249], v[178:181], v[146:161]
	v_mfma_f32_32x32x16_bf16 v[130:145], v[250:253], v[178:181], v[130:145]
	v_add3_u32 v0, s0, v215, v199
	ds_read_b128 v[246:249], v0
	ds_read_b128 v[250:253], v0 offset:8192
	s_waitcnt lgkmcnt(2)
	v_mfma_f32_32x32x16_bf16 v[146:161], v[232:235], v[182:185], v[146:161]
	v_mfma_f32_32x32x16_bf16 v[130:145], v[236:239], v[182:185], v[130:145]
	v_add3_u32 v0, s0, v216, v199
	ds_read_b128 v[232:235], v0
	ds_read_b128 v[236:239], v0 offset:8192
	s_waitcnt lgkmcnt(2)
	v_mfma_f32_32x32x16_bf16 v[146:161], v[246:249], v[186:189], v[146:161]
	v_mfma_f32_32x32x16_bf16 v[130:145], v[250:253], v[186:189], v[130:145]
	s_waitcnt lgkmcnt(0)
	v_mfma_f32_32x32x16_bf16 v[146:161], v[232:235], v[190:193], v[146:161]
	v_mfma_f32_32x32x16_bf16 v[130:145], v[236:239], v[190:193], v[130:145]
	s_setprio 0
	s_nop 7
	s_nop 3
	v_max3_f32 v0, v146, v147, v148
	v_max3_f32 v231, v130, v131, v132
	v_max3_f32 v0, v0, v149, v150
	v_max3_f32 v231, v231, v133, v134
	v_max3_f32 v0, v0, v151, v152
	v_max3_f32 v231, v231, v135, v136
	v_max3_f32 v0, v0, v153, v154
	v_max3_f32 v231, v231, v137, v138
	v_max3_f32 v0, v0, v155, v156
	v_max3_f32 v231, v231, v139, v140
	v_max3_f32 v0, v0, v157, v158
	v_max3_f32 v231, v231, v141, v142
	v_max3_f32 v0, v0, v159, v160
	v_max3_f32 v231, v231, v143, v144
	v_max3_f32 v0, v0, v161, v231
	v_max_f32_e32 v0, v0, v145
	v_mov_b32_e32 v231, v0
	s_nop 1
	v_permlane32_swap_b32_e32 v0, v231
	v_max_f32_e32 v0, v0, v231
	v_sub_f32_e32 v231, v0, v229
	s_mov_b32 s0, 0x42b504f3
	v_cmp_ge_f32_e32 vcc, s0, v231
	v_max_f32_e32 v232, v229, v0
	s_cmp_eq_u64 vcc, exec
	s_cselect_b64 vcc, -1, 0
	v_sub_f32_e32 v0, v229, v232
	v_cndmask_b32_e32 v229, v232, v229, vcc
	v_mul_f32_e32 v231, 0xbe0293ee, v229
	v_fmamk_f32 v146, v146, 0x3e0293ee, v231
	v_fmamk_f32 v147, v147, 0x3e0293ee, v231
	v_fmamk_f32 v148, v148, 0x3e0293ee, v231
	v_fmamk_f32 v149, v149, 0x3e0293ee, v231
	v_fmamk_f32 v150, v150, 0x3e0293ee, v231
	v_fmamk_f32 v151, v151, 0x3e0293ee, v231
	v_fmamk_f32 v152, v152, 0x3e0293ee, v231
	v_fmamk_f32 v153, v153, 0x3e0293ee, v231
	v_fmamk_f32 v154, v154, 0x3e0293ee, v231
	v_fmamk_f32 v155, v155, 0x3e0293ee, v231
	v_fmamk_f32 v156, v156, 0x3e0293ee, v231
	v_fmamk_f32 v157, v157, 0x3e0293ee, v231
	v_fmamk_f32 v158, v158, 0x3e0293ee, v231
	v_fmamk_f32 v159, v159, 0x3e0293ee, v231
	v_fmamk_f32 v160, v160, 0x3e0293ee, v231
	v_fmamk_f32 v161, v161, 0x3e0293ee, v231
	v_fmamk_f32 v130, v130, 0x3e0293ee, v231
	v_fmamk_f32 v131, v131, 0x3e0293ee, v231
	v_fmamk_f32 v132, v132, 0x3e0293ee, v231
	v_fmamk_f32 v133, v133, 0x3e0293ee, v231
	v_fmamk_f32 v134, v134, 0x3e0293ee, v231
	v_fmamk_f32 v135, v135, 0x3e0293ee, v231
	v_fmamk_f32 v136, v136, 0x3e0293ee, v231
	v_fmamk_f32 v137, v137, 0x3e0293ee, v231
	v_fmamk_f32 v138, v138, 0x3e0293ee, v231
	v_fmamk_f32 v139, v139, 0x3e0293ee, v231
	v_fmamk_f32 v140, v140, 0x3e0293ee, v231
	v_fmamk_f32 v141, v141, 0x3e0293ee, v231
	v_fmamk_f32 v142, v142, 0x3e0293ee, v231
	v_fmamk_f32 v143, v143, 0x3e0293ee, v231
	v_fmamk_f32 v144, v144, 0x3e0293ee, v231
	v_fmac_f32_e32 v231, 0x3e0293ee, v145
	v_exp_f32_e32 v145, v146
	v_exp_f32_e32 v146, v147
	v_exp_f32_e32 v147, v148
	v_exp_f32_e32 v148, v149
	v_exp_f32_e32 v149, v150
	v_exp_f32_e32 v150, v151
	v_exp_f32_e32 v151, v152
	v_exp_f32_e32 v152, v153
	v_exp_f32_e32 v153, v154
	v_exp_f32_e32 v154, v155
	v_exp_f32_e32 v155, v156
	v_exp_f32_e32 v156, v157
	v_exp_f32_e32 v157, v158
	v_exp_f32_e32 v158, v159
	v_exp_f32_e32 v159, v160
	v_exp_f32_e32 v160, v161
	v_exp_f32_e32 v161, v134
	v_add_f32_e32 v134, v146, v145
	v_add_f32_e32 v134, v147, v134
	v_add_f32_e32 v134, v148, v134
	v_add_f32_e32 v134, v149, v134
	v_add_f32_e32 v134, v150, v134
	v_add_f32_e32 v134, v151, v134
	v_add_f32_e32 v134, v152, v134
	v_add_f32_e32 v134, v153, v134
	v_add_f32_e32 v134, v154, v134
	v_add_f32_e32 v134, v155, v134
	v_add_f32_e32 v134, v156, v134
	v_exp_f32_e32 v130, v130
	v_add_f32_e32 v134, v157, v134
; __device__ __forceinline__ void finishSM(f32x16& p0, f32x16& p1, float alpha, float& l_reg, bf16x8& pa0, bf16x8& pa1, bf16x8& pa2, bf16x8& pa3) {
; #pragma unroll
;   for (int r = 0; r < 16; ++r) p1[r] = __builtin_amdgcn_exp2f(p1[r]);
;   float ps = 0;
; #pragma unroll
;   for (int r = 0; r < 16; ++r) ps += p0[r];
; #pragma unroll
;   for (int r = 0; r < 16; ++r) ps += p1[r];
;   { auto rr = __builtin_amdgcn_permlane32_swap(__float_as_uint(ps), __float_as_uint(ps), false, false);
;     ps = __uint_as_float(rr[0]) + __uint_as_float(rr[1]); }
;   l_reg = l_reg * alpha + ps;
;     ...
;   PK4(p0, 0, pa0); PK4(p0, 8, pa1); PK4(p1, 0, pa2); PK4(p1, 8, pa3);
;     ...
; }
	v_exp_f32_e32 v131, v131
	v_add_f32_e32 v134, v158, v134
	v_exp_f32_e32 v132, v132
	v_add_f32_e32 v134, v159, v134
	v_exp_f32_e32 v133, v133
	v_add_f32_e32 v134, v160, v134
	v_add_f32_e32 v134, v130, v134
	v_exp_f32_e32 v233, v135
	v_add_f32_e32 v134, v131, v134
	v_exp_f32_e32 v234, v136
	v_add_f32_e32 v134, v132, v134
	v_exp_f32_e32 v235, v137
	v_add_f32_e32 v134, v133, v134
	v_exp_f32_e32 v138, v138
	v_add_f32_e32 v134, v161, v134
	v_exp_f32_e32 v139, v139
	v_add_f32_e32 v134, v233, v134
	v_exp_f32_e32 v140, v140
	v_add_f32_e32 v134, v234, v134
	v_exp_f32_e32 v141, v141
	v_add_f32_e32 v134, v235, v134
	v_exp_f32_e32 v236, v142
	v_add_f32_e32 v134, v138, v134
	v_exp_f32_e32 v237, v143
	v_add_f32_e32 v134, v139, v134
	v_exp_f32_e32 v238, v144
	v_add_f32_e32 v134, v140, v134
	v_mul_f32_e32 v0, 0x3e0293ee, v0
	v_exp_f32_e32 v239, v231
	v_add_f32_e32 v134, v141, v134
	v_exp_f32_e32 v0, v0
	v_add_f32_e32 v134, v236, v134
	v_add_f32_e32 v134, v237, v134
	v_add_f32_e32 v134, v238, v134
	v_add_f32_e32 v231, v239, v134
	v_cndmask_b32_e64 v0, v0, 1.0, vcc
	v_mov_b32_e32 v232, v231
	v_cvt_pk_bf16_f32 v134, v145, v146
	v_cvt_pk_bf16_f32 v135, v147, v148
	v_cvt_pk_bf16_f32 v136, v149, v150
	v_cvt_pk_bf16_f32 v137, v151, v152
	v_cvt_pk_bf16_f32 v142, v153, v154
	v_cvt_pk_bf16_f32 v143, v155, v156
	v_cvt_pk_bf16_f32 v144, v157, v158
	v_cvt_pk_bf16_f32 v145, v159, v160
	v_cvt_pk_bf16_f32 v130, v130, v131
	v_cvt_pk_bf16_f32 v131, v132, v133
	v_cvt_pk_bf16_f32 v132, v161, v233
	v_cvt_pk_bf16_f32 v133, v234, v235
	v_cvt_pk_bf16_f32 v138, v138, v139
	v_cvt_pk_bf16_f32 v139, v140, v141
	v_cvt_pk_bf16_f32 v140, v236, v237
	v_cvt_pk_bf16_f32 v141, v238, v239
	v_permlane32_swap_b32_e32 v231, v232
	v_permlane32_swap_b32_e32 v134, v136
	v_permlane32_swap_b32_e32 v135, v137
	v_permlane32_swap_b32_e32 v142, v144
	v_permlane32_swap_b32_e32 v143, v145
	v_permlane32_swap_b32_e32 v130, v132
	v_permlane32_swap_b32_e32 v131, v133
	v_permlane32_swap_b32_e32 v138, v140
	v_permlane32_swap_b32_e32 v139, v141
	v_cmp_gt_f32_e32 vcc, 1.0, v0
	s_cbranch_vccz .Lpl_649
	s_and_saveexec_b64 s[0:1], s[6:7]
	ds_write_b32 v228, v0 offset:128
	s_or_b64 exec, exec, s[0:1]
	s_waitcnt lgkmcnt(0)
	v_add_u32_e32 v146, s67, v223
	ds_read_b128 v[158:161], v146 offset:224
	ds_read_b128 v[154:157], v146 offset:192
	ds_read_b128 v[150:153], v146 offset:160
	ds_read_b128 v[146:149], v146 offset:128
	s_waitcnt lgkmcnt(0)
	v_pk_mul_f32 v[126:127], v[126:127], v[158:159]
	v_pk_mul_f32 v[122:123], v[122:123], v[154:155]
	v_pk_mul_f32 v[118:119], v[118:119], v[150:151]
	v_pk_mul_f32 v[128:129], v[128:129], v[160:161]
	v_pk_mul_f32 v[124:125], v[124:125], v[156:157]
	v_pk_mul_f32 v[120:121], v[120:121], v[152:153]
	v_pk_mul_f32 v[116:117], v[116:117], v[148:149]
	v_pk_mul_f32 v[114:115], v[114:115], v[146:147]
	v_pk_mul_f32 v[110:111], v[110:111], v[158:159]
	v_pk_mul_f32 v[106:107], v[106:107], v[154:155]
	v_pk_mul_f32 v[102:103], v[102:103], v[150:151]
	v_pk_mul_f32 v[112:113], v[112:113], v[160:161]
	v_pk_mul_f32 v[108:109], v[108:109], v[156:157]
	v_pk_mul_f32 v[104:105], v[104:105], v[152:153]
	v_pk_mul_f32 v[100:101], v[100:101], v[148:149]
	v_pk_mul_f32 v[98:99], v[98:99], v[146:147]
	v_pk_mul_f32 v[94:95], v[94:95], v[158:159]
	v_pk_mul_f32 v[90:91], v[90:91], v[154:155]
	v_pk_mul_f32 v[86:87], v[86:87], v[150:151]
	v_pk_mul_f32 v[96:97], v[96:97], v[160:161]
	v_pk_mul_f32 v[92:93], v[92:93], v[156:157]
	v_pk_mul_f32 v[88:89], v[88:89], v[152:153]
	v_pk_mul_f32 v[84:85], v[84:85], v[148:149]
	v_pk_mul_f32 v[82:83], v[82:83], v[146:147]
	v_pk_mul_f32 v[78:79], v[78:79], v[158:159]
	v_pk_mul_f32 v[74:75], v[74:75], v[154:155]
	v_pk_mul_f32 v[70:71], v[70:71], v[150:151]
	v_pk_mul_f32 v[80:81], v[80:81], v[160:161]
	v_pk_mul_f32 v[76:77], v[76:77], v[156:157]
	v_pk_mul_f32 v[72:73], v[72:73], v[152:153]
	v_pk_mul_f32 v[68:69], v[68:69], v[148:149]
	v_pk_mul_f32 v[66:67], v[66:67], v[146:147]
	v_pk_mul_f32 v[62:63], v[62:63], v[158:159]
	v_pk_mul_f32 v[58:59], v[58:59], v[154:155]
	v_pk_mul_f32 v[54:55], v[54:55], v[150:151]
	v_pk_mul_f32 v[64:65], v[64:65], v[160:161]
	v_pk_mul_f32 v[60:61], v[60:61], v[156:157]
	v_pk_mul_f32 v[56:57], v[56:57], v[152:153]
	v_pk_mul_f32 v[52:53], v[52:53], v[148:149]
	v_pk_mul_f32 v[50:51], v[50:51], v[146:147]
	v_pk_mul_f32 v[46:47], v[46:47], v[158:159]
	v_pk_mul_f32 v[42:43], v[42:43], v[154:155]
	v_pk_mul_f32 v[38:39], v[38:39], v[150:151]
	v_pk_mul_f32 v[48:49], v[48:49], v[160:161]
	v_pk_mul_f32 v[44:45], v[44:45], v[156:157]
	v_pk_mul_f32 v[40:41], v[40:41], v[152:153]
	v_pk_mul_f32 v[36:37], v[36:37], v[148:149]
	v_pk_mul_f32 v[34:35], v[34:35], v[146:147]
	v_pk_mul_f32 v[30:31], v[30:31], v[158:159]
	v_pk_mul_f32 v[26:27], v[26:27], v[154:155]
	v_pk_mul_f32 v[22:23], v[22:23], v[150:151]
	v_pk_mul_f32 v[32:33], v[32:33], v[160:161]
	v_pk_mul_f32 v[28:29], v[28:29], v[156:157]
	v_pk_mul_f32 v[24:25], v[24:25], v[152:153]
	v_pk_mul_f32 v[20:21], v[20:21], v[148:149]
	v_pk_mul_f32 v[18:19], v[18:19], v[146:147]
	v_pk_mul_f32 v[14:15], v[14:15], v[158:159]
	v_pk_mul_f32 v[10:11], v[10:11], v[154:155]
	v_pk_mul_f32 v[6:7], v[6:7], v[150:151]
	v_pk_mul_f32 v[16:17], v[16:17], v[160:161]
	v_pk_mul_f32 v[12:13], v[12:13], v[156:157]
	v_pk_mul_f32 v[8:9], v[8:9], v[152:153]
	v_pk_mul_f32 v[4:5], v[4:5], v[148:149]
	v_pk_mul_f32 v[2:3], v[2:3], v[146:147]
